# speedup vs baseline: 1.0104x; 1.0001x over previous
; __device__ __forceinline__ unsigned cvtpk(float lo, float hi) { f32x2_t v = {lo, hi}; bf16x2_t r = __builtin_convertvector(v, bf16x2_t); return *reinterpret_cast<unsigned*>(&r); }
; #define MFMA(a, b, c) __builtin_amdgcn_mfma_f32_16x16x32_bf16((a), (b), (c), 0, 0, 0)
; __device__ __forceinline__ void phase_dif_attn(const Params& p, char* lds) {
;     ...
;         float rsum = 0.f;
; #pragma unroll
;         for (int n = 0; n < 4; ++n)
; #pragma unroll
;           for (int j = 0; j < 4; ++j) { float pv = __builtin_amdgcn_exp2f(st[mi][n][j] - mnew); st[mi][n][j] = pv; rsum += pv; }
;         lrun[mi] = lrun[mi] * alpha + rsum;
; #pragma unroll
;         for (int ks = 0; ks < 2; ++ks) {
;           u32x4 v = {cvtpk(st[mi][2 * ks][0], st[mi][2 * ks][1]), cvtpk(st[mi][2 * ks][2], st[mi][2 * ks][3]),
;                      cvtpk(st[mi][2 * ks + 1][0], st[mi][2 * ks + 1][1]), cvtpk(st[mi][2 * ks + 1][2], st[mi][2 * ks + 1][3])};
;           pb[mi][ks] = *reinterpret_cast<bf16x8*>(&v);
;         }
;       }
; #pragma unroll
;       for (int dv = 0; dv < 8; ++dv)
; #pragma unroll
;         for (int ks = 0; ks < 2; ++ks) {
;           const char* vp = vbuf + (dv * 16 + l15) * 144 + (ks * 32 + quad * 4) * 2;
;           bf16x4 lo = *(const bf16x4*)vp, hi = *(const bf16x4*)(vp + 32);
;           bf16x8 va = {lo[0], lo[1], lo[2], lo[3], hi[0], hi[1], hi[2], hi[3]};
; #pragma unroll
;           for (int mi = 0; mi < 2; ++mi) oacc[mi][dv] = MFMA(va, pb[mi][ks], oacc[mi][dv]);
;           if (ks == 1 && (dv & 1)) __builtin_amdgcn_sched_barrier(0);
;         }
;       if (kt + 1 < ntile) lwrite((kt + 1) & 1);
;       __syncthreads();
.Lattn_back1:
	v_exp_f32_e32 v120, v120
	v_exp_f32_e32 v104, v104
	v_exp_f32_e32 v121, v121
	v_exp_f32_e32 v105, v105
	v_exp_f32_e32 v122, v122
	v_exp_f32_e32 v106, v106
	v_exp_f32_e32 v123, v123
	v_exp_f32_e32 v107, v107
	v_exp_f32_e32 v116, v116
	v_exp_f32_e32 v100, v100
	v_exp_f32_e32 v117, v117
	v_exp_f32_e32 v101, v101
	v_exp_f32_e32 v118, v118
	v_exp_f32_e32 v102, v102
	v_exp_f32_e32 v119, v119
	v_exp_f32_e32 v103, v103
	v_add_f32_e32 v165, v165, v120
	v_add_f32_e32 v164, v164, v104
	v_add_f32_e32 v165, v165, v121
	v_add_f32_e32 v164, v164, v105
	v_add_f32_e32 v165, v165, v122
	v_add_f32_e32 v164, v164, v106
	v_add_f32_e32 v165, v165, v123
	v_add_f32_e32 v164, v164, v107
	v_add_f32_e32 v165, v165, v116
	v_add_f32_e32 v164, v164, v100
	v_add_f32_e32 v165, v165, v117
	v_add_f32_e32 v164, v164, v101
	v_add_f32_e32 v165, v165, v118
	v_add_f32_e32 v164, v164, v102
	v_add_f32_e32 v165, v165, v119
	v_add_f32_e32 v164, v164, v103
	v_cvt_pk_bf16_f32 v166, v120, v121
	v_cvt_pk_bf16_f32 v167, v122, v123
	v_cvt_pk_bf16_f32 v168, v116, v117
	v_cvt_pk_bf16_f32 v169, v118, v119
	v_cvt_pk_bf16_f32 v170, v104, v105
	v_cvt_pk_bf16_f32 v171, v106, v107
	v_cvt_pk_bf16_f32 v172, v100, v101
	v_cvt_pk_bf16_f32 v173, v102, v103
	v_exp_f32_e32 v112, v112
	v_exp_f32_e32 v96, v96
	s_waitcnt lgkmcnt(12)
	v_mfma_f32_16x16x32_bf16 v[60:63], v[178:181], v[166:169], v[60:63]
	v_exp_f32_e32 v113, v113
	v_exp_f32_e32 v97, v97
	v_exp_f32_e32 v114, v114
	v_mfma_f32_16x16x32_bf16 v[56:59], v[178:181], v[170:173], v[56:59]
	v_exp_f32_e32 v98, v98
	v_exp_f32_e32 v115, v115
	ds_read_b64 v[236:237], v198 offset:24320
	ds_read_b64 v[238:239], v198 offset:24352
	s_waitcnt lgkmcnt(12)
	v_mfma_f32_16x16x32_bf16 v[48:51], v[182:185], v[166:169], v[48:51]
	v_exp_f32_e32 v99, v99
	v_exp_f32_e32 v108, v108
	v_exp_f32_e32 v92, v92
	v_mfma_f32_16x16x32_bf16 v[52:55], v[182:185], v[170:173], v[52:55]
	v_exp_f32_e32 v109, v109
	v_exp_f32_e32 v93, v93
	ds_read_b64 v[178:179], v198 offset:8256
	ds_read_b64 v[180:181], v198 offset:8288
	s_waitcnt lgkmcnt(12)
	v_mfma_f32_16x16x32_bf16 v[44:47], v[186:189], v[166:169], v[44:47]
	v_exp_f32_e32 v110, v110
	v_exp_f32_e32 v94, v94
	v_exp_f32_e32 v111, v111
	v_mfma_f32_16x16x32_bf16 v[40:43], v[186:189], v[170:173], v[40:43]
	v_exp_f32_e32 v95, v95
	v_add_f32_e32 v165, v165, v112
	ds_read_b64 v[182:183], v198 offset:10560
	ds_read_b64 v[184:185], v198 offset:10592
	s_waitcnt lgkmcnt(12)
	v_mfma_f32_16x16x32_bf16 v[36:39], v[190:193], v[166:169], v[36:39]
	v_add_f32_e32 v164, v164, v96
	v_add_f32_e32 v165, v165, v113
	v_add_f32_e32 v164, v164, v97
	v_mfma_f32_16x16x32_bf16 v[32:35], v[190:193], v[170:173], v[32:35]
	v_add_f32_e32 v165, v165, v114
	v_add_f32_e32 v164, v164, v98
	ds_read_b64 v[186:187], v198 offset:12864
	ds_read_b64 v[188:189], v198 offset:12896
	s_waitcnt lgkmcnt(12)
	v_mfma_f32_16x16x32_bf16 v[28:31], v[194:197], v[166:169], v[28:31]
	v_add_f32_e32 v165, v165, v115
	v_add_f32_e32 v164, v164, v99
	v_add_f32_e32 v165, v165, v108
	v_mfma_f32_16x16x32_bf16 v[24:27], v[194:197], v[170:173], v[24:27]
	v_add_f32_e32 v164, v164, v92
	v_add_f32_e32 v165, v165, v109
	ds_read_b64 v[190:191], v198 offset:15168
	ds_read_b64 v[192:193], v198 offset:15200
	s_waitcnt lgkmcnt(12)
	v_mfma_f32_16x16x32_bf16 v[20:23], v[228:231], v[166:169], v[20:23]
	v_add_f32_e32 v164, v164, v93
	v_add_f32_e32 v165, v165, v110
	v_add_f32_e32 v164, v164, v94
	v_mfma_f32_16x16x32_bf16 v[16:19], v[228:231], v[170:173], v[16:19]
	v_add_f32_e32 v165, v165, v111
	v_add_f32_e32 v164, v164, v95
	ds_read_b64 v[194:195], v198 offset:17472
	ds_read_b64 v[196:197], v198 offset:17504
	s_waitcnt lgkmcnt(12)
	v_mfma_f32_16x16x32_bf16 v[12:15], v[232:235], v[166:169], v[12:15]
	v_cvt_pk_bf16_f32 v174, v112, v113
	v_cvt_pk_bf16_f32 v175, v114, v115
	v_cvt_pk_bf16_f32 v176, v108, v109
	v_mfma_f32_16x16x32_bf16 v[8:11], v[232:235], v[170:173], v[8:11]
	v_cvt_pk_bf16_f32 v177, v110, v111
	v_cvt_pk_bf16_f32 v248, v96, v97
	ds_read_b64 v[228:229], v198 offset:19776
	ds_read_b64 v[230:231], v198 offset:19808
	s_waitcnt lgkmcnt(12)
	v_mfma_f32_16x16x32_bf16 v[4:7], v[236:239], v[166:169], v[4:7]
	v_cvt_pk_bf16_f32 v249, v98, v99
	v_cvt_pk_bf16_f32 v250, v92, v93
	v_cvt_pk_bf16_f32 v251, v94, v95
	v_mfma_f32_16x16x32_bf16 v[0:3], v[236:239], v[170:173], v[0:3]
	ds_read_b64 v[232:233], v198 offset:22080
	ds_read_b64 v[234:235], v198 offset:22112
	s_add_i32 s6, s6, 1
	s_waitcnt lgkmcnt(12)
	v_mfma_f32_16x16x32_bf16 v[60:63], v[178:181], v[174:177], v[60:63]
	v_mfma_f32_16x16x32_bf16 v[56:59], v[178:181], v[248:251], v[56:59]
	ds_read_b64 v[236:237], v198 offset:24384
	ds_read_b64 v[238:239], v198 offset:24416
	s_waitcnt lgkmcnt(12)
	v_mfma_f32_16x16x32_bf16 v[48:51], v[182:185], v[174:177], v[48:51]
	v_mfma_f32_16x16x32_bf16 v[52:55], v[182:185], v[248:251], v[52:55]
	s_waitcnt lgkmcnt(10)
	v_mfma_f32_16x16x32_bf16 v[44:47], v[186:189], v[174:177], v[44:47]
	v_mfma_f32_16x16x32_bf16 v[40:43], v[186:189], v[248:251], v[40:43]
	s_bitcmp1_b32 s6, 0
	s_cselect_b32 s8, 0x6800, 0
	s_add_i32 s8, s8, 0
	v_add_u32_e32 v92, s8, v149
	v_add3_u32 v92, v92, v151, v152
	s_waitcnt vmcnt(2)
	ds_write_b128 v92, v[80:83]
	v_add3_u32 v80, s8, v153, v154
	s_add_i32 s7, s7, 64
	s_waitcnt vmcnt(1)
	ds_write_b128 v80, v[84:87] offset:8192
	v_add3_u32 v80, s8, v155, v154
	s_waitcnt vmcnt(0)
	ds_write_b128 v80, v[88:91] offset:8192
	s_waitcnt lgkmcnt(11)
	v_mfma_f32_16x16x32_bf16 v[36:39], v[190:193], v[174:177], v[36:39]
	v_mfma_f32_16x16x32_bf16 v[32:35], v[190:193], v[248:251], v[32:35]
	s_waitcnt lgkmcnt(9)
	v_mfma_f32_16x16x32_bf16 v[28:31], v[194:197], v[174:177], v[28:31]
	v_mfma_f32_16x16x32_bf16 v[24:27], v[194:197], v[248:251], v[24:27]
	s_waitcnt lgkmcnt(7)
	v_mfma_f32_16x16x32_bf16 v[20:23], v[228:231], v[174:177], v[20:23]
	v_mfma_f32_16x16x32_bf16 v[16:19], v[228:231], v[248:251], v[16:19]
	s_waitcnt lgkmcnt(5)
	v_mfma_f32_16x16x32_bf16 v[12:15], v[232:235], v[174:177], v[12:15]
	v_mfma_f32_16x16x32_bf16 v[8:11], v[232:235], v[248:251], v[8:11]
	s_waitcnt lgkmcnt(3)
	v_mfma_f32_16x16x32_bf16 v[4:7], v[236:239], v[174:177], v[4:7]
	v_mfma_f32_16x16x32_bf16 v[0:3], v[236:239], v[248:251], v[0:3]
	s_cmp_eq_u32 s5, s6
	s_waitcnt lgkmcnt(0)
	s_barrier
	s_cbranch_scc1 .Lattn_exit
	s_branch .LBB0_501
.Lattn_exit:
	v_mov_b32_e32 v116, v165
	v_mov_b32_e32 v101, v164
	s_branch .LBB0_508
